# v054 + PE: S5 output GEMM tiles pulled as the last tickets of the phase's work queue (dynamic tail filler) instead of a fixed first job
# baseline (speedup 1.0000x reference)
.Ls5o_entry:
	v_readlane_b32 s4, v251, 45
	v_readlane_b32 s5, v251, 46
	s_load_dwordx2 s[16:17], s[0:1], 0x80
	s_and_b64 s[4:5], s[4:5], exec
	s_movk_i32 s4, 0x80
	s_cselect_b32 s4, s4, 0xa0
	s_waitcnt vmcnt(0)
	v_mov_b32_e32 v4, v0
	s_cmp_eq_u32 s101, 0
	v_readfirstlane_b32 s5, v4
	s_cbranch_scc1 .LBB0_1346
	v_lshlrev_b32_e32 v7, 4, v4
	v_add_u32_e32 v5, 0x2000, v7
	v_ashrrev_i32_e32 v2, 31, v5
	v_lshrrev_b32_e32 v2, 22, v2
	v_add_u32_e32 v2, v5, v2
	v_ashrrev_i32_e32 v2, 10, v2
	v_mul_i32_i24_e32 v6, 0x400, v2
	v_sub_u32_e32 v5, v5, v6
	v_lshrrev_b32_e32 v6, 4, v5
	v_bitop3_b32 v6, v6, v5, 32 bitop3:0x6c
	v_ashrrev_i32_e32 v5, 31, v6
	v_lshrrev_b32_e32 v5, 26, v5
	v_add_u32_e32 v8, v6, v5
	v_lshlrev_b32_e32 v9, 3, v2
	v_ashrrev_i32_e32 v5, 6, v8
	v_and_b32_e32 v9, -16, v9
	v_add_u32_e32 v9, v5, v9
	v_and_b32_e32 v10, 3, v5
	s_mov_b32 s7, 0x3fffe0
	v_lshrrev_b32_e32 v11, 2, v9
	v_lshlrev_b32_e32 v12, 1, v9
	v_and_b32_e32 v8, 0xc0, v8
	v_and_or_b32 v10, v9, s7, v10
	v_and_b32_e32 v11, 4, v11
	v_and_b32_e32 v12, 24, v12
	v_sub_u32_e32 v6, v6, v8
	v_mov_b32_e32 v14, 1
	v_or3_b32 v10, v10, v11, v12
	v_lshlrev_b32_e32 v11, 5, v2
	v_ashrrev_i16_sdwa v6, v14, sext(v6) dst_sel:DWORD dst_unused:UNUSED_PAD src0_sel:DWORD src1_sel:BYTE_0
	v_and_b32_e32 v11, 32, v11
	v_bfe_i32 v6, v6, 0, 16
	v_add_lshl_u32 v8, v11, v6, 1
	v_lshl_add_u32 v172, v10, 10, v8
	v_lshl_add_u32 v174, v9, 15, v8
	v_bfe_i32 v8, v4, 27, 1
	v_lshrrev_b32_e32 v8, 22, v8
	v_add_u32_e32 v8, v7, v8
	v_and_b32_e32 v8, 0xfffffc00, v8
	v_sub_u32_e32 v7, v7, v8
	v_lshrrev_b32_e32 v8, 4, v7
	v_bitop3_b32 v9, v8, v7, 32 bitop3:0x6c
	v_ashrrev_i32_e32 v8, 31, v4
	v_lshrrev_b32_e32 v8, 26, v8
	v_ashrrev_i32_e32 v7, 31, v7
	v_add_u32_e32 v8, v4, v8
	v_lshrrev_b32_e32 v7, 26, v7
	v_ashrrev_i32_e32 v8, 6, v8
	v_add_u32_e32 v7, v9, v7
	v_lshlrev_b32_e32 v10, 3, v8
	v_ashrrev_i32_e32 v7, 6, v7
	v_and_b32_e32 v10, -16, v10
	v_add_u32_e32 v10, v7, v10
	v_and_b32_e32 v11, 3, v7
	v_lshrrev_b32_e32 v12, 2, v10
	v_lshlrev_b32_e32 v13, 1, v10
	v_and_or_b32 v11, v10, s7, v11
	v_and_b32_e32 v12, 4, v12
	v_and_b32_e32 v13, 24, v13
	v_or3_b32 v11, v11, v12, v13
	v_mul_i32_i24_e32 v13, 64, v7
	v_sub_u32_e32 v9, v9, v13
	s_ashr_i32 s10, s5, 6
	v_lshlrev_b32_e32 v12, 5, v8
	v_ashrrev_i16_sdwa v9, v14, sext(v9) dst_sel:DWORD dst_unused:UNUSED_PAD src0_sel:DWORD src1_sel:BYTE_0
	s_lshl_b32 s6, s10, 10
	v_and_b32_e32 v12, 32, v12
	v_bfe_i32 v9, v9, 0, 16
	v_add_lshl_u32 v12, v12, v9, 1
	s_add_i32 s7, s6, 0
	v_readlane_b32 s8, v253, 32
	v_lshl_add_u32 v176, v11, 10, v12
	s_add_i32 m0, s7, 0x10000
	v_readlane_b32 s9, v253, 33
	v_readlane_b32 s12, v253, 8
	v_lshl_add_u32 v178, v10, 15, v12
	v_readlane_b32 s13, v253, 9
	v_readlane_b32 s14, v253, 10
	v_readlane_b32 s15, v253, 11
	global_load_lds_dwordx4 v176, s[8:9]
	s_add_i32 m0, s7, 0x12000
	s_ashr_i32 s11, s5, 8
	global_load_lds_dwordx4 v172, s[8:9]
	s_mov_b32 m0, s7
	s_add_i32 s8, s7, 0x2000
	global_load_lds_dwordx4 v178, s[12:13]
	s_mov_b32 m0, s8
	s_add_i32 s9, s7, 0x4000
	global_load_lds_dwordx4 v174, s[12:13]
	v_readlane_b32 s12, v253, 30
	s_add_i32 m0, s7, 0x14000
	v_readlane_b32 s13, v253, 31
	v_mov_b32_e32 v223, 1
	s_nop 3
	global_load_lds_dwordx4 v176, s[12:13]
	s_add_i32 m0, s7, 0x16000
	s_nop 0
	global_load_lds_dwordx4 v172, s[12:13]
	s_mov_b32 m0, s9
	s_add_i32 s12, s7, 0x6000
	global_load_lds_dwordx4 v178, s[14:15]
	s_mov_b32 m0, s12
	s_cmp_lg_u32 s11, 1
	global_load_lds_dwordx4 v174, s[14:15]
	s_cbranch_scc1 .LBB0_1337
	s_barrier

.LBB0_1346:
	s_mov_b32 s101, 0
	v_readlane_b32 s96, v251, 36
	s_nop 1
	s_ashr_i32 s4, s96, 5
	s_and_b32 s5, s96, 31
	s_nop 1
	v_writelane_b32 v253, s4, 0
	v_writelane_b32 v253, s5, 27
	v_readlane_b32 s6, v253, 2
	v_readlane_b32 s7, v253, 3
	s_lshl_b32 s8, s4, 23
	s_add_u32 s6, s6, s8
	s_addc_u32 s7, s7, 0
	s_lshl_b32 s8, s5, 10
	s_add_u32 s6, s6, s8
	s_addc_u32 s7, s7, 0
	s_nop 1
	v_writelane_b32 v253, s6, 8
	v_writelane_b32 v253, s7, 9
	s_add_u32 s6, s6, 0x400000
	s_addc_u32 s7, s7, 0
	s_nop 1
	v_writelane_b32 v253, s6, 10
	v_writelane_b32 v253, s7, 11
	v_readlane_b32 s6, v253, 28
	v_readlane_b32 s7, v253, 29
	s_lshl_b32 s8, s5, 18
	s_add_u32 s6, s6, s8
	s_addc_u32 s7, s7, 0
	s_nop 1
	v_writelane_b32 v253, s6, 32
	v_writelane_b32 v253, s7, 33
	s_add_u32 s4, s6, 0x20000
	s_addc_u32 s8, s7, 0
	s_nop 1
	v_writelane_b32 v253, s4, 30
	v_writelane_b32 v253, s8, 31
	s_add_u32 s4, s6, 0x20080
	s_addc_u32 s8, s7, 0
	s_nop 1
	v_writelane_b32 v253, s4, 34
	v_writelane_b32 v253, s8, 35
	v_readlane_b32 s4, v251, 34
	v_readlane_b32 s5, v251, 35
	v_readlane_b32 s8, v251, 39
	s_mov_b32 s7, s5
	v_readlane_b32 s9, v251, 40
	s_lshl_b32 s6, s8, 7
	v_writelane_b32 v251, s4, 34
	s_nop 1
	v_writelane_b32 v251, s5, 35
	s_lshl_b64 s[4:5], s[6:7], 2
	s_add_u32 s4, s58, s4
	s_addc_u32 s5, s59, s5
	s_add_u32 s4, s4, 0x8100
	s_addc_u32 s5, s5, 0
	v_writelane_b32 v251, s4, 49
	s_nop 1
	v_writelane_b32 v251, s5, 50
	s_nop 0
	v_readlane_b32 s4, v251, 45
	v_readlane_b32 s5, v251, 46
	s_and_b64 s[4:5], s[4:5], exec
	s_movk_i32 s4, 0x308
	s_cselect_b32 s29, s4, 0x508
	s_mov_b32 s100, s29
	s_movk_i32 s4, 0x80
	s_cselect_b32 s4, s4, 0xa0
	s_add_i32 s29, s29, s4
	s_bitcmp0_b32 s8, 0
	s_mov_b32 s4, 0x9300000
	s_cselect_b32 s4, s4, 0x21900000
	s_lshl_b64 s[6:7], s[8:9], 12
	v_writelane_b32 v251, s6, 51
	s_add_u32 s4, s58, s4
	s_nop 0
	v_writelane_b32 v251, s7, 52
	v_writelane_b32 v251, s4, 53
	s_addc_u32 s4, s59, 0
	v_writelane_b32 v251, s4, 54
	s_lshl_b64 s[4:5], s[8:9], 1
	v_writelane_b32 v251, s4, 43
	s_lshl_b64 s[36:37], s[8:9], 10
	s_nop 0
	v_writelane_b32 v251, s5, 44
	s_lshl_b64 s[4:5], s[8:9], 5
	v_writelane_b32 v251, s4, 55
	s_nop 1
	v_writelane_b32 v251, s5, 56
	v_writelane_b32 v251, s29, 57
	s_branch .LBB0_1349
.Ls5o_call:
	s_sub_i32 s96, s9, s100
	s_ashr_i32 s4, s96, 5
	s_and_b32 s5, s96, 31
	s_nop 1
	v_writelane_b32 v253, s4, 0
	v_writelane_b32 v253, s5, 27
	v_readlane_b32 s6, v253, 2
	v_readlane_b32 s7, v253, 3
	s_lshl_b32 s8, s4, 23
	s_add_u32 s6, s6, s8
	s_addc_u32 s7, s7, 0
	s_lshl_b32 s8, s5, 10
	s_add_u32 s6, s6, s8
	s_addc_u32 s7, s7, 0
	s_nop 1
	v_writelane_b32 v253, s6, 8
	v_writelane_b32 v253, s7, 9
	s_add_u32 s6, s6, 0x400000
	s_addc_u32 s7, s7, 0
	s_nop 1
	v_writelane_b32 v253, s6, 10
	v_writelane_b32 v253, s7, 11
	v_readlane_b32 s6, v253, 28
	v_readlane_b32 s7, v253, 29
	s_lshl_b32 s8, s5, 18
	s_add_u32 s6, s6, s8
	s_addc_u32 s7, s7, 0
	s_nop 1
	v_writelane_b32 v253, s6, 32
	v_writelane_b32 v253, s7, 33
	s_add_u32 s4, s6, 0x20000
	s_addc_u32 s8, s7, 0
	s_nop 1
	v_writelane_b32 v253, s4, 30
	v_writelane_b32 v253, s8, 31
	s_add_u32 s4, s6, 0x20080
	s_addc_u32 s8, s7, 0
	s_nop 1
	v_writelane_b32 v253, s4, 34
	v_writelane_b32 v253, s8, 35
	s_mov_b32 s101, 1
	s_branch .Ls5o_entry

.LBB0_1353:
	s_or_b64 exec, exec, s[16:17]
	v_readlane_b32 s4, v251, 20
	s_waitcnt lgkmcnt(0)
	s_barrier
	v_mov_b32_e32 v2, s4
	ds_read_b32 v2, v2
	s_mov_b64 s[14:15], -1
	s_waitcnt lgkmcnt(0)
	v_cmp_le_i32_e32 vcc, s29, v2
	v_readfirstlane_b32 s9, v2
	s_cbranch_vccnz .LBB0_1348
	s_cmp_ge_i32 s9, s100
	s_cbranch_scc1 .Ls5o_call
	s_cmpk_gt_i32 s9, 0x107
	s_cbranch_scc0 .LBB0_1549
	s_add_i32 s4, s9, 0xfffffef8
	s_and_b32 s5, s4, 0x100
	s_or_b32 s6, s5, 0x4000
	s_lshl_b32 s5, s4, 5
	s_and_b32 s12, s4, 0xff
	s_and_b32 s7, s5, 0x2000
	s_cmpk_lt_u32 s4, 0x200
	s_cselect_b64 s[18:19], -1, 0
	s_and_b64 s[4:5], s[18:19], exec
	s_movk_i32 s4, 0x2000
	s_cselect_b32 s52, s4, 0x100
	s_mul_i32 s4, s12, 0x8400
	v_mov_b32_e32 v59, v0
	v_writelane_b32 v251, s9, 58
	s_cselect_b32 s6, s7, s6
	s_lshl_b32 s4, s4, 1
	v_readlane_b32 s8, v252, 43
	v_readlane_b32 s9, v252, 44
	v_writelane_b32 v251, s4, 59
	s_add_u32 s7, s8, s4
	s_load_dwordx2 s[4:5], s[0:1], 0x98
	s_addc_u32 s8, s9, 0
	s_lshl_b32 s6, s6, 1
	v_writelane_b32 v251, s6, 60
	s_add_u32 s16, s7, s6
	v_readlane_b32 s10, v251, 39
	s_addc_u32 s17, s8, 0
	s_mul_i32 s6, s10, 0x4800
	s_waitcnt lgkmcnt(0)
	s_add_u32 s4, s4, s6
	s_load_dwordx2 s[6:7], s[0:1], 0xa0
	s_mul_hi_u32 s8, s10, 0x4800
	s_addc_u32 s5, s5, s8
	s_lshl_b32 s8, s12, 3
	s_add_u32 s44, s4, s8
	s_addc_u32 s45, s5, 0
	s_mul_i32 s4, s10, 0x1800
	s_waitcnt lgkmcnt(0)
	s_add_u32 s4, s6, s4
	s_mul_hi_u32 s5, s10, 0x1800
	v_mov_b32_e32 v2, s44
	s_addc_u32 s5, s7, s5
	v_add_co_u32_e32 v6, vcc, 0x1000, v2
	v_mov_b32_e32 v9, s45
	s_add_u32 s26, s4, s8
	v_addc_co_u32_e32 v7, vcc, 0, v9, vcc
	s_addc_u32 s27, s5, 0
	v_mov_b64_e32 v[4:5], s[44:45]
	v_add_co_u32_e32 v8, vcc, 0x3000, v2
	v_lshlrev_b32_e32 v52, 3, v59
	s_nop 0
	v_addc_co_u32_e32 v9, vcc, 0, v9, vcc
	flat_load_dword v89, v[4:5]
	flat_load_dword v83, v[6:7] offset:2048
	flat_load_dword v85, v[8:9]
	v_mov_b64_e32 v[4:5], s[26:27]
	flat_load_dword v87, v[4:5]
	v_cmp_gt_i32_e64 s[34:35], s52, v52
	v_mov_b32_e32 v64, 0
	v_mov_b32_e32 v43, 0
	v_ashrrev_i32_e32 v53, 31, v52
	v_mov_b32_e32 v42, 0
	v_mov_b32_e32 v41, 0
	v_mov_b32_e32 v40, 0
	v_mov_b32_e32 v65, 0
	v_readlane_b32 s11, v251, 40
	s_and_saveexec_b64 s[38:39], s[34:35]
	s_cbranch_execz .LBB0_1361
	v_lshl_add_u64 v[4:5], v[52:53], 1, s[16:17]
	global_load_dwordx4 v[40:43], v[4:5], off
	v_cmp_lt_i32_e32 vcc, 0, v52
	v_mov_b32_e32 v65, 0
	v_mov_b32_e32 v64, 0
	s_and_saveexec_b64 s[14:15], vcc
	s_cbranch_execz .LBB0_1358
	v_mov_b32_e32 v2, v52
	v_lshl_add_u64 v[6:7], v[2:3], 1, s[16:17]
	global_load_ushort v64, v[6:7], off offset:-2
